# p@w_ple_proj GEMM spread over all 32 workgroups of a group (one tile each) in layers 0-2, where the upper half also converts weights
# baseline (speedup 1.0000x reference)
; template <bool F16, class Sched, class Epi>
; __device__ __forceinline__ void gemm_phase(LAS unsigned char* lds, const Gemm g, const Sched& S, const Epi& E, int wave_s) {
;     const int tid = tid_now(wave_s);
;     const int wid = __builtin_amdgcn_readfirstlane(tid >> 6), lane = tid & 63, wr = wid >> 2, wc = wid & 3, fr = lane & 15, fq = lane >> 4;
;     const int K = g.K, nt = K / BK, lda = g.lda;
;     unsigned voffA[2], voffB[2];
; #pragma unroll
;     for (int i = 0; i < 2; ++i) { int R, C; stage_rc(tid * 16 + i * 8192, R, C); const int Rb = (R & ~31) + perm32(R & 31);
;         voffA[i] = (unsigned)(R * lda + C) * 2u; voffB[i] = (unsigned)(Rb * K + C) * 2u; }
;     const size_t kstep = (size_t)(BK * 2);
;     const size_t hstepA = (size_t)HALF * lda * 2, hstepB = (size_t)HALF * K * 2;
;     const size_t tstepA = 2 * hstepA, tstepB = 2 * hstepB;
;     const unsigned ldsw = (unsigned)wid * 1024u;
;     const int aoff = lds_byte(wr * 64 + fr, fq * 8), boff = lds_byte(wc * 32 + fr, fq * 8);
;     ...
;     Unit cur, nxt; int ui = 0;
;     if (!S.next(0, cur)) return;
;     f32x4 acc[2][2][4][2];
; #pragma unroll
;     for (int a = 0; a < 2; ++a)
; #pragma unroll
;         for (int b = 0; b < 2; ++b)
; #pragma unroll
;             for (int m = 0; m < 4; ++m)
; #pragma unroll
;                 for (int n = 0; n < 2; ++n) acc[a][b][m][n] = (f32x4){0.f, 0.f, 0.f, 0.f};
;     bf16x8 At[4][2], B0[2][2], B1[2][2];
;     const char* cA = (const char*)g.A + PG8_AOFF(cur); const char* cB = (const char*)g.Bt + (size_t)cur.pn * tstepB;
;     PG8_STAGE(PG8_SB(0, 0), cB, voffB); PG8_STAGE(PG8_SB(0, 1), cB + hstepB, voffB); PG8_STAGE(PG8_SA(0, 0), cA, voffA); PG8_STAGE(PG8_SA(0, 1), cA + hstepA, voffA);
;     if (wr == 1) PG8_BAR;
;     PG8_WAIT_V(2); PG8_BAR;
;     PG8_STAGE(PG8_SB(1, 0), cB + kstep, voffB); PG8_STAGE(PG8_SA(1, 0), cA + kstep, voffA); PG8_STAGE(PG8_SB(1, 1), cB + hstepB + kstep, voffB);
;     PG8_WAIT_V(6); PG8_BAR;
;     for (;;) {
;         const bool has_next = S.next(ui + 1, nxt);
;         const char* nA = has_next ? (const char*)g.A + PG8_AOFF(nxt) : cA + (size_t)(nt - 2) * kstep; const char* nB = has_next ? (const char*)g.Bt + (size_t)nxt.pn * tstepB : cB + (size_t)(nt - 2) * kstep;
; __global__ void __launch_bounds__(NWAVES * 64, 2) fwd_megakernel(Args args_unused) {
;     ...
;             pg8::GroupOrder S; S.init(0, D / 256, GS / 2, GC - GS / 2, GRP);
.LBB0_688:
	s_mov_b64 s[0:1], s[78:79]
	s_mov_b32 s2, s75
	s_ashr_i32 s2, s2, 3
	s_sub_i32 s12, s2, s87
	s_cmp_eq_u32 s20, 3
	s_cselect_b32 s12, s12, s2
	s_mov_b32 s2, s75
	v_mbcnt_lo_u32_b32 v8, -1, 0
	v_mbcnt_hi_u32_b32 v8, -1, v8
	s_cmp_gt_u32 s12, 31
	v_add_u32_e32 v0, s80, v8
	s_nop 0
	v_readfirstlane_b32 s10, v0
	s_cbranch_scc1 .LBB0_700
	v_lshlrev_b32_e32 v1, 4, v0
	v_add_u32_e32 v2, 0x2000, v1
	v_ashrrev_i32_e32 v3, 31, v2
	v_lshrrev_b32_e32 v3, 22, v3
	v_add_u32_e32 v3, v2, v3
	v_ashrrev_i32_e32 v3, 10, v3
	v_mul_i32_i24_e32 v4, 0x400, v3
	v_sub_u32_e32 v2, v2, v4
	v_lshrrev_b32_e32 v4, 4, v2
	v_bitop3_b32 v2, v4, v2, 32 bitop3:0x6c
	v_ashrrev_i32_e32 v4, 31, v2
	v_lshrrev_b32_e32 v4, 26, v4
	v_add_u32_e32 v4, v2, v4
	v_lshlrev_b32_e32 v6, 3, v3
	v_ashrrev_i32_e32 v5, 6, v4
	v_and_b32_e32 v6, -16, v6
	v_and_b32_e32 v4, 0xc0, v4
	s_lshl_b32 s2, s2, 2
	v_add_u32_e32 v6, v5, v6
	v_sub_u32_e32 v2, v2, v4
	s_and_b32 s34, s2, 28
	v_and_b32_e32 v5, 3, v5
	s_mov_b32 s2, 0x7fffe0
	v_lshrrev_b32_e32 v7, 2, v6
	v_lshlrev_b32_e32 v9, 1, v6
	v_lshlrev_b32_e32 v3, 5, v3
	v_ashrrev_i16_sdwa v2, v234, sext(v2) dst_sel:DWORD dst_unused:UNUSED_PAD src0_sel:DWORD src1_sel:BYTE_0
	s_load_dwordx2 s[8:9], s[0:1], 0xa0
	v_and_or_b32 v5, v6, s2, v5
	v_and_b32_e32 v7, 4, v7
	v_and_b32_e32 v9, 24, v9
	v_and_b32_e32 v3, 32, v3
	v_bfe_i32 v2, v2, 0, 16
	v_or3_b32 v5, v5, v7, v9
	v_add_lshl_u32 v2, v3, v2, 1
	v_lshl_add_u32 v128, v5, 9, v2
	v_lshl_add_u32 v130, v6, 9, v2
	v_bfe_i32 v2, v0, 27, 1
	v_lshrrev_b32_e32 v2, 22, v2
	s_lshl_b64 s[0:1], s[20:21], 22
	v_add_u32_e32 v2, v1, v2
	s_waitcnt lgkmcnt(0)
	s_add_u32 s0, s8, s0
	v_and_b32_e32 v2, 0xfffffc00, v2
	s_addc_u32 s1, s9, s1
	v_sub_u32_e32 v1, v1, v2
	s_add_u32 s35, s0, 0x17000000
	v_lshrrev_b32_e32 v2, 4, v1
	v_ashrrev_i32_e32 v4, 31, v0
	s_addc_u32 s36, s1, 0
	s_lshl_b64 s[0:1], s[20:21], 20
	v_bitop3_b32 v1, v2, v1, 32 bitop3:0x6c
	v_lshrrev_b32_e32 v4, 26, v4
	s_add_u32 s0, s8, s0
	v_ashrrev_i32_e32 v2, 31, v1
	v_add_u32_e32 v0, v0, v4
	s_addc_u32 s1, s9, s1
	v_lshrrev_b32_e32 v2, 26, v2
	v_ashrrev_i32_e32 v0, 6, v0
	s_add_u32 s37, s0, 0x16c00000
	v_add_u32_e32 v2, v1, v2
	v_lshlrev_b32_e32 v4, 3, v0
	s_addc_u32 s38, s1, 0
	s_and_b32 s0, s12, 3
	v_ashrrev_i32_e32 v3, 6, v2
	v_and_b32_e32 v4, -16, v4
	v_and_b32_e32 v2, 0xc0, v2
	s_ashr_i32 s11, s10, 6
	s_or_b32 s0, s34, s0
	s_lshr_b32 s1, s12, 2
	v_add_u32_e32 v4, v3, v4
	v_and_b32_e32 v3, 3, v3
	v_sub_u32_e32 v1, v1, v2
	s_ashr_i32 s13, s10, 8
	s_lshl_b32 s39, s11, 10
	v_and_or_b32 v3, v4, s2, v3
	v_lshrrev_b32_e32 v5, 2, v4
	v_lshlrev_b32_e32 v6, 1, v4
	v_lshlrev_b32_e32 v0, 5, v0
	v_ashrrev_i16_sdwa v1, v234, sext(v1) dst_sel:DWORD dst_unused:UNUSED_PAD src0_sel:DWORD src1_sel:BYTE_0
	s_lshl_b32 s14, s0, 17
	s_lshl_b32 s2, s1, 17
	v_and_b32_e32 v5, 4, v5
	v_and_b32_e32 v6, 24, v6
	v_and_b32_e32 v0, 32, v0
	v_bfe_i32 v1, v1, 0, 16
	s_add_u32 s2, s37, s2
	v_or3_b32 v3, v3, v5, v6
	v_add_lshl_u32 v0, v0, v1, 1
	s_addc_u32 s3, s38, 0
	s_add_i32 s41, s39, 0
	v_lshl_add_u32 v176, v3, 9, v0
	s_add_i32 m0, s41, 0x10000
	v_lshl_add_u32 v132, v4, 9, v0
	global_load_lds_dwordx4 v176, s[2:3]
	s_add_i32 m0, s41, 0x12000
	s_add_u32 s6, s2, 0x10000
	global_load_lds_dwordx4 v128, s[2:3]
	s_addc_u32 s7, s3, 0
	s_add_i32 m0, s41, 0x14000
	v_mov_b32_e32 v129, v177
	global_load_lds_dwordx4 v176, s[6:7]
	s_add_i32 m0, s41, 0x16000
	s_add_u32 s24, s35, s14
	s_addc_u32 s25, s36, 0
	s_add_i32 s42, s41, 0x2000
	global_load_lds_dwordx4 v128, s[6:7]
	s_mov_b32 m0, s41
	s_add_u32 s6, s24, 0x10000
	global_load_lds_dwordx4 v132, s[24:25]
	s_mov_b32 m0, s42
	s_addc_u32 s7, s25, 0
	s_add_i32 s43, s41, 0x4000
	global_load_lds_dwordx4 v130, s[24:25]
	s_mov_b32 m0, s43
	s_add_i32 s44, s41, 0x6000
	global_load_lds_dwordx4 v132, s[6:7]
	s_mov_b32 m0, s44
	v_mov_b32_e32 v133, v177
	global_load_lds_dwordx4 v130, s[6:7]
	v_mov_b32_e32 v131, v177
	s_cmp_eq_u32 s13, 1
	v_mov_b32_e32 v205, 0x1fff
	v_mov_b32_e32 v254, 0x2000
	v_mov_b32_e32 v197, 1
	v_lshl_add_u64 v[6:7], s[2:3], 0, v[176:177]
	v_lshl_add_u64 v[4:5], s[2:3], 0, v[128:129]
	v_lshl_add_u64 v[0:1], s[24:25], 0, v[132:133]
	s_cselect_b64 s[6:7], -1, 0
	s_cmp_lg_u32 s13, 1
	v_lshl_add_u64 v[2:3], s[24:25], 0, v[130:131]
	s_cbranch_scc1 .LBB0_691
	s_barrier
.LBB0_691:
	v_lshrrev_b32_e32 v10, 1, v8
	v_and_b32_e32 v10, 24, v10
	s_add_u32 s8, s8, 0x22000000
	v_and_b32_e32 v9, 15, v8
	v_lshlrev_b32_e32 v11, 1, v10
	v_lshlrev_b32_e32 v8, 2, v8
	s_addc_u32 s9, s9, 0
	v_lshl_or_b32 v136, s13, 6, v9
	v_lshl_or_b32 v9, v9, 6, v11
	s_lshl_b32 s13, s13, 13
	v_and_b32_e32 v8, 32, v8
	s_lshl_b32 s11, s11, 5
	v_bitop3_b32 v11, v9, s13, v8 bitop3:0xde
	s_and_b32 s13, s11, 0x60
	s_add_i32 m0, s41, 0x18000
	v_lshl_add_u64 v[6:7], v[6:7], 0, s[54:55]
	s_lshl_b32 s11, s13, 7
	s_waitcnt vmcnt(2)
	s_barrier
	global_load_lds_dwordx4 v[6:7], off
	v_lshl_add_u64 v[4:5], v[4:5], 0, s[54:55]
	s_add_i32 m0, s41, 0x1a000
	s_add_i32 s45, s41, 0x8000
	s_add_i32 s46, s41, 0xa000
	global_load_lds_dwordx4 v[4:5], off
	v_lshl_add_u64 v[0:1], v[0:1], 0, s[54:55]
	s_mov_b32 m0, s45
	s_add_u32 s14, s2, 0x10080
	global_load_lds_dwordx4 v[0:1], off
	v_lshl_add_u64 v[0:1], v[2:3], 0, s[54:55]
	s_mov_b32 m0, s46
	s_addc_u32 s15, s3, 0
	global_load_lds_dwordx4 v[0:1], off
	s_add_i32 m0, s41, 0x1c000
	v_lshl_add_u64 v[0:1], s[14:15], 0, v[176:177]
	global_load_lds_dwordx4 v[0:1], off
	v_lshl_add_u64 v[0:1], s[14:15], 0, v[128:129]
	s_add_i32 m0, s41, 0x1e000
	s_cmpk_lt_u32 s10, 0x100
	global_load_lds_dwordx4 v[0:1], off
	s_waitcnt vmcnt(6)
	v_bitop3_b32 v137, v9, s11, v8 bitop3:0xde
	s_cselect_b64 s[10:11], -1, 0
	v_or_b32_e32 v138, s13, v10
	s_cmp_eq_u32 s20, 3
	s_cselect_b32 s32, s87, 32
	s_add_i32 s47, s32, s12
	v_add_u32_e32 v139, 0, v11
	s_barrier
	s_branch .LBB0_694
.LBB0_692:
	s_cmp_eq_u32 s20, 3
	s_cselect_b32 s32, s87, 32
	s_add_i32 s47, s47, s32
	s_mov_b64 s[0:1], 0
